# P0 weight transpose: W_in items issue all 32 weight + 32 gain loads pipelined with counted waits (was one load pair + wait per row pair)
# speedup vs baseline: 1.0213x; 1.0213x over previous
; #define DUPREP(k) for (int rep_ = 0; rep_ < 1 + ((MK_DUP >> (k)) & 1); ++rep_)
; #define LAS __attribute__((address_space(3)))
; #define LDS_WAIT() asm volatile("s_waitcnt lgkmcnt(0)" ::: "memory")
; __device__ __forceinline__ void p0_transpose_item(const float* W, int K, int N, bf16_t* WT, LAS float* scr, int item, int lane, const float* kscale) {
;     const int nblk = N / 32, kb = item / nblk, nb = item % nblk, k0 = 64 * kb, n0 = 32 * nb;
; #pragma unroll 8
;     for (int i = 0; i < 32; ++i) { const int kk = 2 * i + (lane >> 5); scr[kk * 33 + (lane & 31)] = W[(size_t)(k0 + kk) * N + n0 + (lane & 31)] * (kscale ? kscale[k0 + kk] : 1.0f); }
;     LDS_WAIT(); asm volatile("" ::: "memory");
; __global__ void __launch_bounds__(512, 2) mk_fwd(Params p) {
;     ...
;             DUPREP(0) for (int it = gw; it < DEPTH * IL; it += NGW) {
;                 const int l = it / IL, r = it % IL;
;                 if (r < I1) p0_transpose_item(p.w_in + (size_t)l * DM * DIN, DM, DIN, W1T + (size_t)l * DIN * DM, scr, r, lane, p.norm_w + (size_t)l * DM);
.LBB0_230:
	s_and_b64 vcc, exec, s[0:1]
	s_cbranch_vccz .LBB0_225
	s_lshl_b64 s[0:1], s[2:3], 13
	s_add_u32 s18, s54, s0
	s_mul_i32 s0, s5, 0x4ec5
	s_addc_u32 s19, s55, s1
	s_lshr_b32 s1, s0, 31
	s_ashr_i32 s0, s0, 22
	s_add_i32 s0, s0, s1
	s_mul_i32 s1, s0, 0xd0
	s_sub_i32 s1, s5, s1
	s_sext_i32_i16 s1, s1
	s_lshl_b32 s16, s1, 5
	s_lshl_b32 s20, s0, 6
	s_ashr_i32 s17, s16, 31
	s_mul_i32 s7, s2, 0x3400000
	s_ashr_i32 s21, s20, 31
	s_lshl_b64 s[0:1], s[16:17], 2
	s_mul_hi_i32 s6, s2, 0x3400000
	s_add_u32 s0, s0, s7
	s_addc_u32 s1, s1, s6
	s_mul_i32 s8, s20, 0x6800
	s_add_u32 s6, s56, s0
	s_addc_u32 s7, s57, s1
	s_add_u32 s6, s6, s8
	s_addc_u32 s7, s7, 0
	v_mov_b32_e32 v47, 0x6800
	v_mad_u32_u24 v47, v4, v47, v12
	v_or_b32_e32 v32, s20, v4
	v_lshlrev_b32_e32 v32, 2, v32
	v_mov_b32_e32 v33, v1
	v_lshl_add_u64 v[32:33], s[18:19], 0, v[32:33]
	global_load_dword v100, v47, s[6:7]
	s_add_u32 s6, s6, 0xd000
	s_addc_u32 s7, s7, 0
	global_load_dword v132, v[32:33], off offset:0
	global_load_dword v101, v47, s[6:7]
	s_add_u32 s6, s6, 0xd000
	s_addc_u32 s7, s7, 0
	global_load_dword v133, v[32:33], off offset:8
	global_load_dword v102, v47, s[6:7]
	s_add_u32 s6, s6, 0xd000
	s_addc_u32 s7, s7, 0
	global_load_dword v134, v[32:33], off offset:16
	global_load_dword v103, v47, s[6:7]
	s_add_u32 s6, s6, 0xd000
	s_addc_u32 s7, s7, 0
	global_load_dword v135, v[32:33], off offset:24
	global_load_dword v104, v47, s[6:7]
	s_add_u32 s6, s6, 0xd000
	s_addc_u32 s7, s7, 0
	global_load_dword v136, v[32:33], off offset:32
	global_load_dword v105, v47, s[6:7]
	s_add_u32 s6, s6, 0xd000
	s_addc_u32 s7, s7, 0
	global_load_dword v137, v[32:33], off offset:40
	global_load_dword v106, v47, s[6:7]
	s_add_u32 s6, s6, 0xd000
	s_addc_u32 s7, s7, 0
	global_load_dword v138, v[32:33], off offset:48
	global_load_dword v107, v47, s[6:7]
	s_add_u32 s6, s6, 0xd000
	s_addc_u32 s7, s7, 0
	global_load_dword v139, v[32:33], off offset:56
	global_load_dword v108, v47, s[6:7]
	s_add_u32 s6, s6, 0xd000
	s_addc_u32 s7, s7, 0
	global_load_dword v140, v[32:33], off offset:64
	global_load_dword v109, v47, s[6:7]
	s_add_u32 s6, s6, 0xd000
	s_addc_u32 s7, s7, 0
	global_load_dword v141, v[32:33], off offset:72
	global_load_dword v110, v47, s[6:7]
	s_add_u32 s6, s6, 0xd000
	s_addc_u32 s7, s7, 0
	global_load_dword v142, v[32:33], off offset:80
	global_load_dword v111, v47, s[6:7]
	s_add_u32 s6, s6, 0xd000
	s_addc_u32 s7, s7, 0
	global_load_dword v143, v[32:33], off offset:88
	global_load_dword v112, v47, s[6:7]
	s_add_u32 s6, s6, 0xd000
	s_addc_u32 s7, s7, 0
	global_load_dword v144, v[32:33], off offset:96
	global_load_dword v113, v47, s[6:7]
	s_add_u32 s6, s6, 0xd000
	s_addc_u32 s7, s7, 0
	global_load_dword v145, v[32:33], off offset:104
	global_load_dword v114, v47, s[6:7]
	s_add_u32 s6, s6, 0xd000
	s_addc_u32 s7, s7, 0
	global_load_dword v146, v[32:33], off offset:112
	global_load_dword v115, v47, s[6:7]
	s_add_u32 s6, s6, 0xd000
	s_addc_u32 s7, s7, 0
	global_load_dword v147, v[32:33], off offset:120
	global_load_dword v116, v47, s[6:7]
	s_add_u32 s6, s6, 0xd000
	s_addc_u32 s7, s7, 0
	global_load_dword v148, v[32:33], off offset:128
	s_waitcnt vmcnt(32)
	v_mul_f32_e32 v100, v100, v132
	ds_write_b32 v39, v100 offset:0
	global_load_dword v117, v47, s[6:7]
	s_add_u32 s6, s6, 0xd000
	s_addc_u32 s7, s7, 0
	global_load_dword v149, v[32:33], off offset:136
	s_waitcnt vmcnt(32)
	v_mul_f32_e32 v101, v101, v133
	ds_write_b32 v39, v101 offset:264
	global_load_dword v118, v47, s[6:7]
	s_add_u32 s6, s6, 0xd000
	s_addc_u32 s7, s7, 0
	global_load_dword v150, v[32:33], off offset:144
	s_waitcnt vmcnt(32)
	v_mul_f32_e32 v102, v102, v134
	ds_write_b32 v39, v102 offset:528
	global_load_dword v119, v47, s[6:7]
	s_add_u32 s6, s6, 0xd000
	s_addc_u32 s7, s7, 0
	global_load_dword v151, v[32:33], off offset:152
	s_waitcnt vmcnt(32)
	v_mul_f32_e32 v103, v103, v135
	ds_write_b32 v39, v103 offset:792
	global_load_dword v120, v47, s[6:7]
	s_add_u32 s6, s6, 0xd000
	s_addc_u32 s7, s7, 0
	global_load_dword v152, v[32:33], off offset:160
	s_waitcnt vmcnt(32)
; #define LDS_WAIT() asm volatile("s_waitcnt lgkmcnt(0)" ::: "memory")
; __device__ __forceinline__ void p0_transpose_item(const float* W, int K, int N, bf16_t* WT, LAS float* scr, int item, int lane, const float* kscale) {
;     ...
;     for (int i = 0; i < 32; ++i) { const int kk = 2 * i + (lane >> 5); scr[kk * 33 + (lane & 31)] = W[(size_t)(k0 + kk) * N + n0 + (lane & 31)] * (kscale ? kscale[k0 + kk] : 1.0f); }
;     LDS_WAIT(); asm volatile("" ::: "memory");
	v_mul_f32_e32 v104, v104, v136
	ds_write_b32 v39, v104 offset:1056
	global_load_dword v121, v47, s[6:7]
	s_add_u32 s6, s6, 0xd000
	s_addc_u32 s7, s7, 0
	global_load_dword v153, v[32:33], off offset:168
	s_waitcnt vmcnt(32)
	v_mul_f32_e32 v105, v105, v137
	ds_write_b32 v39, v105 offset:1320
	global_load_dword v122, v47, s[6:7]
	s_add_u32 s6, s6, 0xd000
	s_addc_u32 s7, s7, 0
	global_load_dword v154, v[32:33], off offset:176
	s_waitcnt vmcnt(32)
	v_mul_f32_e32 v106, v106, v138
	ds_write_b32 v39, v106 offset:1584
	global_load_dword v123, v47, s[6:7]
	s_add_u32 s6, s6, 0xd000
	s_addc_u32 s7, s7, 0
	global_load_dword v155, v[32:33], off offset:184
	s_waitcnt vmcnt(32)
	v_mul_f32_e32 v107, v107, v139
	ds_write_b32 v39, v107 offset:1848
	global_load_dword v124, v47, s[6:7]
	s_add_u32 s6, s6, 0xd000
	s_addc_u32 s7, s7, 0
	global_load_dword v156, v[32:33], off offset:192
	s_waitcnt vmcnt(32)
	v_mul_f32_e32 v108, v108, v140
	ds_write_b32 v39, v108 offset:2112
	global_load_dword v125, v47, s[6:7]
	s_add_u32 s6, s6, 0xd000
	s_addc_u32 s7, s7, 0
	global_load_dword v157, v[32:33], off offset:200
	s_waitcnt vmcnt(32)
	v_mul_f32_e32 v109, v109, v141
	ds_write_b32 v39, v109 offset:2376
	global_load_dword v126, v47, s[6:7]
	s_add_u32 s6, s6, 0xd000
	s_addc_u32 s7, s7, 0
	global_load_dword v158, v[32:33], off offset:208
	s_waitcnt vmcnt(32)
	v_mul_f32_e32 v110, v110, v142
	ds_write_b32 v39, v110 offset:2640
	global_load_dword v127, v47, s[6:7]
	s_add_u32 s6, s6, 0xd000
	s_addc_u32 s7, s7, 0
	global_load_dword v159, v[32:33], off offset:216
	s_waitcnt vmcnt(32)
	v_mul_f32_e32 v111, v111, v143
	ds_write_b32 v39, v111 offset:2904
	global_load_dword v128, v47, s[6:7]
	s_add_u32 s6, s6, 0xd000
	s_addc_u32 s7, s7, 0
	global_load_dword v160, v[32:33], off offset:224
	s_waitcnt vmcnt(32)
	v_mul_f32_e32 v112, v112, v144
	ds_write_b32 v39, v112 offset:3168
	global_load_dword v129, v47, s[6:7]
	s_add_u32 s6, s6, 0xd000
	s_addc_u32 s7, s7, 0
	global_load_dword v161, v[32:33], off offset:232
	s_waitcnt vmcnt(32)
	v_mul_f32_e32 v113, v113, v145
	ds_write_b32 v39, v113 offset:3432
	global_load_dword v130, v47, s[6:7]
	s_add_u32 s6, s6, 0xd000
	s_addc_u32 s7, s7, 0
	global_load_dword v162, v[32:33], off offset:240
	s_waitcnt vmcnt(32)
	v_mul_f32_e32 v114, v114, v146
	ds_write_b32 v39, v114 offset:3696
	global_load_dword v131, v47, s[6:7]
	global_load_dword v163, v[32:33], off offset:248
	s_waitcnt vmcnt(32)
	v_mul_f32_e32 v115, v115, v147
	ds_write_b32 v39, v115 offset:3960
	s_waitcnt vmcnt(30)
	v_mul_f32_e32 v116, v116, v148
	ds_write_b32 v39, v116 offset:4224
	s_waitcnt vmcnt(28)
	v_mul_f32_e32 v117, v117, v149
	ds_write_b32 v39, v117 offset:4488
	s_waitcnt vmcnt(26)
	v_mul_f32_e32 v118, v118, v150
	ds_write_b32 v39, v118 offset:4752
	s_waitcnt vmcnt(24)
	v_mul_f32_e32 v119, v119, v151
	ds_write_b32 v39, v119 offset:5016
	s_waitcnt vmcnt(22)
	v_mul_f32_e32 v120, v120, v152
	ds_write_b32 v39, v120 offset:5280
	s_waitcnt vmcnt(20)
	v_mul_f32_e32 v121, v121, v153
	ds_write_b32 v39, v121 offset:5544
	s_waitcnt vmcnt(18)
	v_mul_f32_e32 v122, v122, v154
	ds_write_b32 v39, v122 offset:5808
	s_waitcnt vmcnt(16)
	v_mul_f32_e32 v123, v123, v155
	ds_write_b32 v39, v123 offset:6072
	s_waitcnt vmcnt(14)
	v_mul_f32_e32 v124, v124, v156
	ds_write_b32 v39, v124 offset:6336
	s_waitcnt vmcnt(12)
	v_mul_f32_e32 v125, v125, v157
	ds_write_b32 v39, v125 offset:6600
	s_waitcnt vmcnt(10)
	v_mul_f32_e32 v126, v126, v158
	ds_write_b32 v39, v126 offset:6864
	s_waitcnt vmcnt(8)
	v_mul_f32_e32 v127, v127, v159
	ds_write_b32 v39, v127 offset:7128
	s_waitcnt vmcnt(6)
	v_mul_f32_e32 v128, v128, v160
	ds_write_b32 v39, v128 offset:7392
	s_waitcnt vmcnt(4)
	v_mul_f32_e32 v129, v129, v161
	ds_write_b32 v39, v129 offset:7656
	s_waitcnt vmcnt(2)
	v_mul_f32_e32 v130, v130, v162
	ds_write_b32 v39, v130 offset:7920
	s_waitcnt vmcnt(0)
	v_mul_f32_e32 v131, v131, v163
	ds_write_b32 v39, v131 offset:8184
	s_branch .LBB0_224
